# weight conversion loops (both instances) hand-written: scalar tile decode, dwordx4 global loads instead of flat dword loads, two tiles in flight, double-buffered LDS transpose
# speedup vs baseline: 1.0550x; 1.0037x over previous
.LBB0_48:
	s_or_b64 exec, exec, s[40:41]
	v_readlane_b32 s0, v254, 27
	s_waitcnt lgkmcnt(0)
	s_barrier
	v_mov_b32_e32 v10, 0x10540
	ds_read_b32 v46, v10
	v_mov_b32_e32 v11, 0x10424
	ds_read_b32 v47, v11
	ds_read_b32 v48, v11 offset:40
	ds_read_b32 v49, v11 offset:80
	ds_read_b32 v50, v11 offset:120
	ds_read_b32 v51, v11 offset:160
	ds_read_b32 v52, v11 offset:200
	ds_read_b32 v53, v11 offset:240
	v_mov_b32_e32 v9, 0x10400
	ds_read_b64 v[54:55], v9
	v_readlane_b32 s0, v252, 59
	v_readlane_b32 s1, v252, 60
	s_load_dword s28, s[0:1], 0x0
	v_readlane_b32 s16, v252, 58
	s_waitcnt lgkmcnt(0)
	v_readfirstlane_b32 s34, v46
	v_readfirstlane_b32 s35, v47
	v_readfirstlane_b32 s36, v48
	v_readfirstlane_b32 s37, v49
	v_readfirstlane_b32 s38, v50
	v_readfirstlane_b32 s39, v51
	v_readfirstlane_b32 s40, v52
	v_readfirstlane_b32 s41, v53
	v_readfirstlane_b32 s50, v54
	v_readfirstlane_b32 s51, v55
	s_nop 3
	s_add_i32 s34, s34, -1
	s_mov_b32 s33, s35
	s_cmp_eq_u32 s34, 1
	s_cselect_b32 s33, s36, s33
	s_cmp_eq_u32 s34, 2
	s_cselect_b32 s33, s37, s33
	s_cmp_eq_u32 s34, 3
	s_cselect_b32 s33, s38, s33
	s_cmp_eq_u32 s34, 4
	s_cselect_b32 s33, s39, s33
	s_cmp_eq_u32 s34, 5
	s_cselect_b32 s33, s40, s33
	s_cmp_eq_u32 s34, 6
	s_cselect_b32 s33, s41, s33
	s_lshr_b32 s0, s16, 4
	s_cmp_ge_i32 s0, s33
	s_cbranch_scc1 .Lcv_exit
	v_lshrrev_b32_e32 v1, 4, v155
	v_and_b32_e32 v2, 15, v155
	v_lshlrev_b32_e32 v2, 4, v2
	v_lshrrev_b32_e32 v4, 3, v155
	v_and_b32_e32 v5, 7, v155
	v_lshlrev_b32_e32 v5, 4, v5
	v_bfe_u32 v10, v4, 2, 1
	v_lshlrev_b32_e32 v6, 4, v10
	v_bfe_u32 v10, v4, 3, 2
	v_lshl_add_u32 v6, v10, 2, v6
	v_and_b32_e32 v10, 3, v4
	v_add_u32_e32 v6, v6, v10
	v_and_b32_e32 v10, 32, v4
	v_add_u32_e32 v6, v6, v10
	s_movk_i32 s42, 0x104
	v_mad_u32_u24 v3, v1, s42, v2
	v_add_u32_e32 v40, 0x2080, v3
	v_add_u32_e32 v41, 0x4100, v3
	v_add_u32_e32 v42, 0x4100, v40
	v_and_b32_e32 v10, 7, v155
	s_movk_i32 s42, 0x820
	v_mul_u32_u24_e32 v10, s42, v10
	v_lshl_add_u32 v7, v4, 2, v10
	v_add_u32_e32 v43, 0x410, v7
	v_add_u32_e32 v44, 0x4100, v7
	v_add_u32_e32 v45, 0x4100, v43
	s_mov_b32 s29, s0
	s_cmp_ge_i32 s29, s33
	s_cbranch_scc1 .Lcv_ip1
	s_mov_b32 s42, 0
	s_cmp_ge_i32 s29, s35
	s_cselect_b32 s43, 1, 0
	s_cmp_gt_u32 s34, 0
	s_cselect_b32 s43, s43, 0
	s_add_i32 s42, s42, s43
	s_cmp_ge_i32 s29, s36
	s_cselect_b32 s43, 1, 0
	s_cmp_gt_u32 s34, 1
	s_cselect_b32 s43, s43, 0
	s_add_i32 s42, s42, s43
	s_cmp_ge_i32 s29, s37
	s_cselect_b32 s43, 1, 0
	s_cmp_gt_u32 s34, 2
	s_cselect_b32 s43, s43, 0
	s_add_i32 s42, s42, s43
	s_cmp_ge_i32 s29, s38
	s_cselect_b32 s43, 1, 0
	s_cmp_gt_u32 s34, 3
	s_cselect_b32 s43, s43, 0
	s_add_i32 s42, s42, s43
	s_cmp_ge_i32 s29, s39
	s_cselect_b32 s43, 1, 0
	s_cmp_gt_u32 s34, 4
	s_cselect_b32 s43, s43, 0
	s_add_i32 s42, s42, s43
	s_cmp_ge_i32 s29, s40
	s_cselect_b32 s43, 1, 0
	s_cmp_gt_u32 s34, 5
	s_cselect_b32 s43, s43, 0
	s_add_i32 s42, s42, s43
	s_mul_i32 s42, s42, 40
	s_add_i32 s42, s42, 0x10400
	v_mov_b32_e32 v10, s42
	ds_read_b64 v[46:47], v10
	ds_read_b64 v[48:49], v10 offset:8
	ds_read_b64 v[50:51], v10 offset:16
	ds_read_b64 v[52:53], v10 offset:24
	ds_read_b32 v54, v10 offset:32
	s_waitcnt lgkmcnt(0)
	v_readfirstlane_b32 s50, v46
	v_readfirstlane_b32 s51, v47
	v_readfirstlane_b32 s52, v48
	v_readfirstlane_b32 s53, v49
	v_readfirstlane_b32 s68, v50
	v_readfirstlane_b32 s69, v51
	v_readfirstlane_b32 s100, v52
	v_readfirstlane_b32 s70, v53
	v_readfirstlane_b32 s101, v54
	s_nop 3
	s_sub_i32 s43, s29, s101
	s_lshr_b32 s100, s100, 6
	s_movk_i32 s101, 0x1000
	s_cmp_eq_u32 s100, 24
	s_cselect_b32 s101, 0xaab, s101
	s_cmp_eq_u32 s100, 44
	s_cselect_b32 s101, 0x5d2, s101
	s_mul_i32 s1, s43, s101
	s_lshr_b32 s1, s1, 16
	s_mul_i32 s16, s1, s100
	s_sub_i32 s16, s43, s16
	s_mul_i32 s42, s1, s68
	s_lshl_b32 s42, s42, 8
	s_lshl_b32 s43, s16, 8
	s_add_u32 s42, s42, s43
	s_add_u32 s50, s50, s42
	s_addc_u32 s51, s51, 0
	s_lshl_b32 s43, s68, 7
	s_add_u32 s52, s50, s43
	s_addc_u32 s53, s51, 0
	s_lshl_b32 s43, s68, 2
	v_mad_u32_u24 v8, v1, s43, v2
.Lcv_ip1:
	s_cmp_ge_i32 s29, s33
	s_cbranch_scc1 .Lcv_dm2
	global_load_dwordx4 v[12:15], v8, s[50:51] nt
	global_load_dwordx4 v[16:19], v8, s[52:53] nt
	s_branch .Lcv_dn3
.Lcv_dm2:
	global_load_dwordx4 v[12:15], v2, s[50:51]
	global_load_dwordx4 v[16:19], v2, s[50:51]
.Lcv_dn3:
	s_add_i32 s29, s29, s28
	s_cmp_ge_i32 s29, s33
	s_cbranch_scc1 .Lcv_ip4
	s_mov_b32 s42, 0
	s_cmp_ge_i32 s29, s35
	s_cselect_b32 s43, 1, 0
	s_cmp_gt_u32 s34, 0
	s_cselect_b32 s43, s43, 0
	s_add_i32 s42, s42, s43
	s_cmp_ge_i32 s29, s36
	s_cselect_b32 s43, 1, 0
	s_cmp_gt_u32 s34, 1
	s_cselect_b32 s43, s43, 0
	s_add_i32 s42, s42, s43
	s_cmp_ge_i32 s29, s37
	s_cselect_b32 s43, 1, 0
	s_cmp_gt_u32 s34, 2
	s_cselect_b32 s43, s43, 0
	s_add_i32 s42, s42, s43
	s_cmp_ge_i32 s29, s38
	s_cselect_b32 s43, 1, 0
	s_cmp_gt_u32 s34, 3
	s_cselect_b32 s43, s43, 0
	s_add_i32 s42, s42, s43
	s_cmp_ge_i32 s29, s39
	s_cselect_b32 s43, 1, 0
	s_cmp_gt_u32 s34, 4
	s_cselect_b32 s43, s43, 0
	s_add_i32 s42, s42, s43
	s_cmp_ge_i32 s29, s40
	s_cselect_b32 s43, 1, 0
	s_cmp_gt_u32 s34, 5
	s_cselect_b32 s43, s43, 0
	s_add_i32 s42, s42, s43
	s_mul_i32 s42, s42, 40
	s_add_i32 s42, s42, 0x10400
	v_mov_b32_e32 v10, s42
	ds_read_b64 v[46:47], v10
	ds_read_b64 v[48:49], v10 offset:8
	ds_read_b64 v[50:51], v10 offset:16
	ds_read_b64 v[52:53], v10 offset:24
	ds_read_b32 v54, v10 offset:32
	s_waitcnt lgkmcnt(0)
	v_readfirstlane_b32 s50, v46
	v_readfirstlane_b32 s51, v47
	v_readfirstlane_b32 s52, v48
	v_readfirstlane_b32 s53, v49
	v_readfirstlane_b32 s68, v50
	v_readfirstlane_b32 s69, v51
	v_readfirstlane_b32 s100, v52
	v_readfirstlane_b32 s70, v53
	v_readfirstlane_b32 s101, v54
	s_nop 3
	s_sub_i32 s43, s29, s101
	s_lshr_b32 s100, s100, 6
	s_movk_i32 s101, 0x1000
	s_cmp_eq_u32 s100, 24
	s_cselect_b32 s101, 0xaab, s101
	s_cmp_eq_u32 s100, 44
	s_cselect_b32 s101, 0x5d2, s101
	s_mul_i32 s1, s43, s101
	s_lshr_b32 s1, s1, 16
	s_mul_i32 s16, s1, s100
	s_sub_i32 s16, s43, s16
	s_mul_i32 s42, s1, s68
	s_lshl_b32 s42, s42, 8
	s_lshl_b32 s43, s16, 8
	s_add_u32 s42, s42, s43
	s_add_u32 s50, s50, s42
	s_addc_u32 s51, s51, 0
	s_lshl_b32 s43, s68, 7
	s_add_u32 s52, s50, s43
	s_addc_u32 s53, s51, 0
	s_lshl_b32 s43, s68, 2
	v_mad_u32_u24 v8, v1, s43, v2
.Lcv_ip4:
	s_cmp_ge_i32 s29, s33
	s_cbranch_scc1 .Lcv_dm5
	global_load_dwordx4 v[20:23], v8, s[50:51] nt
	global_load_dwordx4 v[24:27], v8, s[52:53] nt
	s_branch .Lcv_dn6
.Lcv_dm5:
	global_load_dwordx4 v[20:23], v2, s[50:51]
	global_load_dwordx4 v[24:27], v2, s[50:51]
.Lcv_dn6:
	s_add_i32 s29, s29, s28
	s_mov_b32 s42, 0
	s_cmp_ge_i32 s0, s35
	s_cselect_b32 s43, 1, 0
	s_cmp_gt_u32 s34, 0
	s_cselect_b32 s43, s43, 0
	s_add_i32 s42, s42, s43
	s_cmp_ge_i32 s0, s36
	s_cselect_b32 s43, 1, 0
	s_cmp_gt_u32 s34, 1
	s_cselect_b32 s43, s43, 0
	s_add_i32 s42, s42, s43
	s_cmp_ge_i32 s0, s37
	s_cselect_b32 s43, 1, 0
	s_cmp_gt_u32 s34, 2
	s_cselect_b32 s43, s43, 0
	s_add_i32 s42, s42, s43
	s_cmp_ge_i32 s0, s38
	s_cselect_b32 s43, 1, 0
	s_cmp_gt_u32 s34, 3
	s_cselect_b32 s43, s43, 0
	s_add_i32 s42, s42, s43
	s_cmp_ge_i32 s0, s39
	s_cselect_b32 s43, 1, 0
	s_cmp_gt_u32 s34, 4
	s_cselect_b32 s43, s43, 0
	s_add_i32 s42, s42, s43
	s_cmp_ge_i32 s0, s40
	s_cselect_b32 s43, 1, 0
	s_cmp_gt_u32 s34, 5
	s_cselect_b32 s43, s43, 0
	s_add_i32 s42, s42, s43
	s_mul_i32 s42, s42, 40
	s_add_i32 s42, s42, 0x10400
	v_mov_b32_e32 v10, s42
	ds_read_b64 v[46:47], v10
	ds_read_b64 v[48:49], v10 offset:8
	ds_read_b64 v[50:51], v10 offset:16
	ds_read_b64 v[52:53], v10 offset:24
	ds_read_b32 v54, v10 offset:32
	s_waitcnt lgkmcnt(0)
	v_readfirstlane_b32 s50, v46
	v_readfirstlane_b32 s51, v47
	v_readfirstlane_b32 s52, v48
	v_readfirstlane_b32 s53, v49
	v_readfirstlane_b32 s68, v50
	v_readfirstlane_b32 s69, v51
	v_readfirstlane_b32 s100, v52
	v_readfirstlane_b32 s70, v53
	v_readfirstlane_b32 s101, v54
	s_nop 3
	s_sub_i32 s43, s0, s101
	s_lshr_b32 s100, s100, 6
	s_movk_i32 s101, 0x1000
	s_cmp_eq_u32 s100, 24
	s_cselect_b32 s101, 0xaab, s101
	s_cmp_eq_u32 s100, 44
	s_cselect_b32 s101, 0x5d2, s101
	s_mul_i32 s1, s43, s101
	s_lshr_b32 s1, s1, 16
	s_mul_i32 s16, s1, s100
	s_sub_i32 s16, s43, s16
	s_lshl_b32 s42, s16, 6
	s_mov_b32 vcc_lo, 1
	s_cmp_eq_u32 s70, 3
	s_cselect_b32 s43, 1, 0
	s_cmp_ge_u32 s16, 16
	s_cselect_b32 s43, s43, 0
	s_cmp_eq_u32 s43, 1
	s_cselect_b32 vcc_lo, 0, vcc_lo
	s_lshr_b32 s43, s16, 1
	s_lshl_b32 s43, s43, 8
	s_and_b32 vcc_hi, s16, 1
	s_lshl_b32 vcc_hi, vcc_hi, 6
	s_add_i32 s43, s43, vcc_hi
	s_cmp_eq_u32 s70, 1
	s_cselect_b32 s42, s43, s42
	s_add_i32 s43, s43, 0x80
	s_cmp_eq_u32 s70, 2
	s_cselect_b32 s42, s43, s42
	s_mul_i32 s42, s42, s69
	s_lshl_b32 s43, s1, 6
	s_add_i32 s42, s42, s43
	s_lshl_b32 s42, s42, 1
	s_add_u32 s52, s52, s42
	s_addc_u32 s53, s53, 0
	s_cmp_eq_u32 vcc_lo, 0
	s_cbranch_scc1 .Lcv_pl7
	v_mov_b32_e32 v11, v6
	s_branch .Lcv_pd8
.Lcv_pl7:
	v_mov_b32_e32 v11, v4
.Lcv_pd8:
	s_lshl_b32 s43, s69, 1
	v_mad_u32_u24 v9, v11, s43, v5
	s_mov_b64 s[54:55], s[52:53]
	s_cmp_ge_i32 s29, s33
	s_cbranch_scc1 .Lcv_ip9
	s_mov_b32 s42, 0
	s_cmp_ge_i32 s29, s35
	s_cselect_b32 s43, 1, 0
	s_cmp_gt_u32 s34, 0
	s_cselect_b32 s43, s43, 0
	s_add_i32 s42, s42, s43
	s_cmp_ge_i32 s29, s36
	s_cselect_b32 s43, 1, 0
	s_cmp_gt_u32 s34, 1
	s_cselect_b32 s43, s43, 0
	s_add_i32 s42, s42, s43
	s_cmp_ge_i32 s29, s37
	s_cselect_b32 s43, 1, 0
	s_cmp_gt_u32 s34, 2
	s_cselect_b32 s43, s43, 0
	s_add_i32 s42, s42, s43
	s_cmp_ge_i32 s29, s38
	s_cselect_b32 s43, 1, 0
	s_cmp_gt_u32 s34, 3
	s_cselect_b32 s43, s43, 0
	s_add_i32 s42, s42, s43
	s_cmp_ge_i32 s29, s39
	s_cselect_b32 s43, 1, 0
	s_cmp_gt_u32 s34, 4
	s_cselect_b32 s43, s43, 0
	s_add_i32 s42, s42, s43
	s_cmp_ge_i32 s29, s40
	s_cselect_b32 s43, 1, 0
	s_cmp_gt_u32 s34, 5
	s_cselect_b32 s43, s43, 0
	s_add_i32 s42, s42, s43
	s_mul_i32 s42, s42, 40
	s_add_i32 s42, s42, 0x10400
	v_mov_b32_e32 v10, s42
	ds_read_b64 v[46:47], v10
	ds_read_b64 v[48:49], v10 offset:8
	ds_read_b64 v[50:51], v10 offset:16
	ds_read_b64 v[52:53], v10 offset:24
	ds_read_b32 v54, v10 offset:32
	s_waitcnt lgkmcnt(0)
	v_readfirstlane_b32 s50, v46
	v_readfirstlane_b32 s51, v47
	v_readfirstlane_b32 s52, v48
	v_readfirstlane_b32 s53, v49
	v_readfirstlane_b32 s68, v50
	v_readfirstlane_b32 s69, v51
	v_readfirstlane_b32 s100, v52
	v_readfirstlane_b32 s70, v53
	v_readfirstlane_b32 s101, v54
	s_nop 3
	s_sub_i32 s43, s29, s101
	s_lshr_b32 s100, s100, 6
	s_movk_i32 s101, 0x1000
	s_cmp_eq_u32 s100, 24
	s_cselect_b32 s101, 0xaab, s101
	s_cmp_eq_u32 s100, 44
	s_cselect_b32 s101, 0x5d2, s101
	s_mul_i32 s1, s43, s101
	s_lshr_b32 s1, s1, 16
	s_mul_i32 s16, s1, s100
	s_sub_i32 s16, s43, s16
	s_mul_i32 s42, s1, s68
	s_lshl_b32 s42, s42, 8
	s_lshl_b32 s43, s16, 8
	s_add_u32 s42, s42, s43
	s_add_u32 s50, s50, s42
	s_addc_u32 s51, s51, 0
	s_lshl_b32 s43, s68, 7
	s_add_u32 s52, s50, s43
	s_addc_u32 s53, s51, 0
	s_lshl_b32 s43, s68, 2
	v_mad_u32_u24 v8, v1, s43, v2
.Lcv_ip9:
	s_waitcnt vmcnt(2)
	ds_write2_b32 v3, v12, v13 offset1:1
	ds_write2_b32 v3, v14, v15 offset0:2 offset1:3
	ds_write2_b32 v40, v16, v17 offset1:1
	ds_write2_b32 v40, v18, v19 offset0:2 offset1:3
	s_cmp_ge_i32 s29, s33
	s_cbranch_scc1 .Lcv_dm10
	global_load_dwordx4 v[12:15], v8, s[50:51] nt
	global_load_dwordx4 v[16:19], v8, s[52:53] nt
	s_branch .Lcv_dn11

.Lcv_dn11:
	s_waitcnt lgkmcnt(0)
	s_barrier
	s_add_i32 s29, s29, s28
	ds_read2_b32 v[28:29], v7 offset1:65
	ds_read2_b32 v[30:31], v7 offset0:130 offset1:195
	ds_read2_b32 v[32:33], v43 offset1:65
	ds_read2_b32 v[34:35], v43 offset0:130 offset1:195
	s_waitcnt lgkmcnt(0)
	v_cvt_pk_bf16_f32 v36, v28, v29
	v_cvt_pk_bf16_f32 v37, v30, v31
	v_cvt_pk_bf16_f32 v38, v32, v33
	v_cvt_pk_bf16_f32 v39, v34, v35
	global_store_dwordx4 v9, v[36:39], s[54:55]
	s_add_i32 s0, s0, s28
	s_cmp_ge_i32 s0, s33
	s_cbranch_scc1 .Lcv_exit
	s_mov_b32 s42, 0
	s_cmp_ge_i32 s0, s35
	s_cselect_b32 s43, 1, 0
	s_cmp_gt_u32 s34, 0
	s_cselect_b32 s43, s43, 0
	s_add_i32 s42, s42, s43
	s_cmp_ge_i32 s0, s36
	s_cselect_b32 s43, 1, 0
	s_cmp_gt_u32 s34, 1
	s_cselect_b32 s43, s43, 0
	s_add_i32 s42, s42, s43
	s_cmp_ge_i32 s0, s37
	s_cselect_b32 s43, 1, 0
	s_cmp_gt_u32 s34, 2
	s_cselect_b32 s43, s43, 0
	s_add_i32 s42, s42, s43
	s_cmp_ge_i32 s0, s38
	s_cselect_b32 s43, 1, 0
	s_cmp_gt_u32 s34, 3
	s_cselect_b32 s43, s43, 0
	s_add_i32 s42, s42, s43
	s_cmp_ge_i32 s0, s39
	s_cselect_b32 s43, 1, 0
	s_cmp_gt_u32 s34, 4
	s_cselect_b32 s43, s43, 0
	s_add_i32 s42, s42, s43
	s_cmp_ge_i32 s0, s40
	s_cselect_b32 s43, 1, 0
	s_cmp_gt_u32 s34, 5
	s_cselect_b32 s43, s43, 0
	s_add_i32 s42, s42, s43
	s_mul_i32 s42, s42, 40
	s_add_i32 s42, s42, 0x10400
	v_mov_b32_e32 v10, s42
	ds_read_b64 v[46:47], v10
	ds_read_b64 v[48:49], v10 offset:8
	ds_read_b64 v[50:51], v10 offset:16
	ds_read_b64 v[52:53], v10 offset:24
	ds_read_b32 v54, v10 offset:32
	s_waitcnt lgkmcnt(0)
	v_readfirstlane_b32 s50, v46
	v_readfirstlane_b32 s51, v47
	v_readfirstlane_b32 s52, v48
	v_readfirstlane_b32 s53, v49
	v_readfirstlane_b32 s68, v50
	v_readfirstlane_b32 s69, v51
	v_readfirstlane_b32 s100, v52
	v_readfirstlane_b32 s70, v53
	v_readfirstlane_b32 s101, v54
	s_nop 3
	s_sub_i32 s43, s0, s101
	s_lshr_b32 s100, s100, 6
	s_movk_i32 s101, 0x1000
	s_cmp_eq_u32 s100, 24
	s_cselect_b32 s101, 0xaab, s101
	s_cmp_eq_u32 s100, 44
	s_cselect_b32 s101, 0x5d2, s101
	s_mul_i32 s1, s43, s101
	s_lshr_b32 s1, s1, 16
	s_mul_i32 s16, s1, s100
	s_sub_i32 s16, s43, s16
	s_lshl_b32 s42, s16, 6
	s_mov_b32 vcc_lo, 1
	s_cmp_eq_u32 s70, 3
	s_cselect_b32 s43, 1, 0
	s_cmp_ge_u32 s16, 16
	s_cselect_b32 s43, s43, 0
	s_cmp_eq_u32 s43, 1
	s_cselect_b32 vcc_lo, 0, vcc_lo
	s_lshr_b32 s43, s16, 1
	s_lshl_b32 s43, s43, 8
	s_and_b32 vcc_hi, s16, 1
	s_lshl_b32 vcc_hi, vcc_hi, 6
	s_add_i32 s43, s43, vcc_hi
	s_cmp_eq_u32 s70, 1
	s_cselect_b32 s42, s43, s42
	s_add_i32 s43, s43, 0x80
	s_cmp_eq_u32 s70, 2
	s_cselect_b32 s42, s43, s42
	s_mul_i32 s42, s42, s69
	s_lshl_b32 s43, s1, 6
	s_add_i32 s42, s42, s43
	s_lshl_b32 s42, s42, 1
	s_add_u32 s52, s52, s42
	s_addc_u32 s53, s53, 0
	s_cmp_eq_u32 vcc_lo, 0
	s_cbranch_scc1 .Lcv_pl12
	v_mov_b32_e32 v11, v6
	s_branch .Lcv_pd13

.Lcv_ip14:
	s_waitcnt vmcnt(3)
	ds_write2_b32 v41, v20, v21 offset1:1
	ds_write2_b32 v41, v22, v23 offset0:2 offset1:3
	ds_write2_b32 v42, v24, v25 offset1:1
	ds_write2_b32 v42, v26, v27 offset0:2 offset1:3
	s_cmp_ge_i32 s29, s33
	s_cbranch_scc1 .Lcv_dm15
	global_load_dwordx4 v[20:23], v8, s[50:51] nt
	global_load_dwordx4 v[24:27], v8, s[52:53] nt
	s_branch .Lcv_dn16

.Lcv_dn16:
	s_waitcnt lgkmcnt(0)
	s_barrier
	s_add_i32 s29, s29, s28
	ds_read2_b32 v[28:29], v44 offset1:65
	ds_read2_b32 v[30:31], v44 offset0:130 offset1:195
	ds_read2_b32 v[32:33], v45 offset1:65
	ds_read2_b32 v[34:35], v45 offset0:130 offset1:195
	s_waitcnt lgkmcnt(0)
	v_cvt_pk_bf16_f32 v36, v28, v29
	v_cvt_pk_bf16_f32 v37, v30, v31
	v_cvt_pk_bf16_f32 v38, v32, v33
	v_cvt_pk_bf16_f32 v39, v34, v35
	global_store_dwordx4 v9, v[36:39], s[54:55]
	s_add_i32 s0, s0, s28
	s_cmp_ge_i32 s0, s33
	s_cbranch_scc1 .Lcv_exit
.Lcv_loop:
	s_mov_b32 s42, 0
	s_cmp_ge_i32 s0, s35
	s_cselect_b32 s43, 1, 0
	s_cmp_gt_u32 s34, 0
	s_cselect_b32 s43, s43, 0
	s_add_i32 s42, s42, s43
	s_cmp_ge_i32 s0, s36
	s_cselect_b32 s43, 1, 0
	s_cmp_gt_u32 s34, 1
	s_cselect_b32 s43, s43, 0
	s_add_i32 s42, s42, s43
	s_cmp_ge_i32 s0, s37
	s_cselect_b32 s43, 1, 0
	s_cmp_gt_u32 s34, 2
	s_cselect_b32 s43, s43, 0
	s_add_i32 s42, s42, s43
	s_cmp_ge_i32 s0, s38
	s_cselect_b32 s43, 1, 0
	s_cmp_gt_u32 s34, 3
	s_cselect_b32 s43, s43, 0
	s_add_i32 s42, s42, s43
	s_cmp_ge_i32 s0, s39
	s_cselect_b32 s43, 1, 0
	s_cmp_gt_u32 s34, 4
	s_cselect_b32 s43, s43, 0
	s_add_i32 s42, s42, s43
	s_cmp_ge_i32 s0, s40
	s_cselect_b32 s43, 1, 0
	s_cmp_gt_u32 s34, 5
	s_cselect_b32 s43, s43, 0
	s_add_i32 s42, s42, s43
	s_mul_i32 s42, s42, 40
	s_add_i32 s42, s42, 0x10400
	v_mov_b32_e32 v10, s42
	ds_read_b64 v[46:47], v10
	ds_read_b64 v[48:49], v10 offset:8
	ds_read_b64 v[50:51], v10 offset:16
	ds_read_b64 v[52:53], v10 offset:24
	ds_read_b32 v54, v10 offset:32
	s_waitcnt lgkmcnt(0)
	v_readfirstlane_b32 s50, v46
	v_readfirstlane_b32 s51, v47
	v_readfirstlane_b32 s52, v48
	v_readfirstlane_b32 s53, v49
	v_readfirstlane_b32 s68, v50
	v_readfirstlane_b32 s69, v51
	v_readfirstlane_b32 s100, v52
	v_readfirstlane_b32 s70, v53
	v_readfirstlane_b32 s101, v54
	s_nop 3
	s_sub_i32 s43, s0, s101
	s_lshr_b32 s100, s100, 6
	s_movk_i32 s101, 0x1000
	s_cmp_eq_u32 s100, 24
	s_cselect_b32 s101, 0xaab, s101
	s_cmp_eq_u32 s100, 44
	s_cselect_b32 s101, 0x5d2, s101
	s_mul_i32 s1, s43, s101
	s_lshr_b32 s1, s1, 16
	s_mul_i32 s16, s1, s100
	s_sub_i32 s16, s43, s16
	s_lshl_b32 s42, s16, 6
	s_mov_b32 vcc_lo, 1
	s_cmp_eq_u32 s70, 3
	s_cselect_b32 s43, 1, 0
	s_cmp_ge_u32 s16, 16
	s_cselect_b32 s43, s43, 0
	s_cmp_eq_u32 s43, 1
	s_cselect_b32 vcc_lo, 0, vcc_lo
	s_lshr_b32 s43, s16, 1
	s_lshl_b32 s43, s43, 8
	s_and_b32 vcc_hi, s16, 1
	s_lshl_b32 vcc_hi, vcc_hi, 6
	s_add_i32 s43, s43, vcc_hi
	s_cmp_eq_u32 s70, 1
	s_cselect_b32 s42, s43, s42
	s_add_i32 s43, s43, 0x80
	s_cmp_eq_u32 s70, 2
	s_cselect_b32 s42, s43, s42
	s_mul_i32 s42, s42, s69
	s_lshl_b32 s43, s1, 6
	s_add_i32 s42, s42, s43
	s_lshl_b32 s42, s42, 1
	s_add_u32 s52, s52, s42
	s_addc_u32 s53, s53, 0
	s_cmp_eq_u32 vcc_lo, 0
	s_cbranch_scc1 .Lcv_pl17
	v_mov_b32_e32 v11, v6
	s_branch .Lcv_pd18

.Lcv_ip19:
	s_waitcnt vmcnt(4)
	ds_write2_b32 v3, v12, v13 offset1:1
	ds_write2_b32 v3, v14, v15 offset0:2 offset1:3
	ds_write2_b32 v40, v16, v17 offset1:1
	ds_write2_b32 v40, v18, v19 offset0:2 offset1:3
	s_cmp_ge_i32 s29, s33
	s_cbranch_scc1 .Lcv_dm20
	global_load_dwordx4 v[12:15], v8, s[50:51] nt
	global_load_dwordx4 v[16:19], v8, s[52:53] nt
	s_branch .Lcv_dn21

.Lcv_ip24:
	s_waitcnt vmcnt(4)
	ds_write2_b32 v41, v20, v21 offset1:1
	ds_write2_b32 v41, v22, v23 offset0:2 offset1:3
	ds_write2_b32 v42, v24, v25 offset1:1
	ds_write2_b32 v42, v26, v27 offset0:2 offset1:3
	s_cmp_ge_i32 s29, s33
	s_cbranch_scc1 .Lcv_dm25
	global_load_dwordx4 v[20:23], v8, s[50:51] nt
	global_load_dwordx4 v[24:27], v8, s[52:53] nt
	s_branch .Lcv_dn26

.Lcv_dn26:
	s_waitcnt lgkmcnt(0)
	s_barrier
	s_add_i32 s29, s29, s28
	ds_read2_b32 v[28:29], v44 offset1:65
	ds_read2_b32 v[30:31], v44 offset0:130 offset1:195
	ds_read2_b32 v[32:33], v45 offset1:65
	ds_read2_b32 v[34:35], v45 offset0:130 offset1:195
	s_waitcnt lgkmcnt(0)
	v_cvt_pk_bf16_f32 v36, v28, v29
	v_cvt_pk_bf16_f32 v37, v30, v31
	v_cvt_pk_bf16_f32 v38, v32, v33
	v_cvt_pk_bf16_f32 v39, v34, v35
	global_store_dwordx4 v9, v[36:39], s[54:55]
	s_add_i32 s0, s0, s28
	s_cmp_ge_i32 s0, s33
	s_cbranch_scc1 .Lcv_exit
	s_branch .Lcv_loop
.Lcv_exit:
	s_branch .LBB0_107
	v_mov_b32_e32 v0, s0
	ds_read_b32 v0, v0
	v_readlane_b32 s1, v254, 52
	v_mov_b32_e32 v30, 0
	v_mov_b32_e32 v29, 0
	v_mov_b32_e32 v28, 0
	s_waitcnt lgkmcnt(0)
	v_mul_lo_u32 v1, v0, 40
	v_add_u32_e32 v1, 0, v1
	v_add_u32_e32 v1, 0x103fc, v1
	ds_read_b32 v1, v1
	v_readfirstlane_b32 s29, v0
	v_mov_b32_e32 v27, 0
	v_mov_b32_e32 v26, 0
	v_mov_b32_e32 v25, 0
	s_waitcnt lgkmcnt(0)
	v_cmp_ge_i32_e32 vcc, s1, v1
	v_readfirstlane_b32 s0, v1
	v_cmp_lt_i32_e64 s[40:41], s1, v1
	v_mov_b32_e32 v24, 0
	v_mov_b32_e32 v3, 0
	s_cbranch_vccnz .LBB0_55
	s_cmp_lt_i32 s29, 2
	s_mov_b32 s34, 0
	s_cbranch_scc1 .LBB0_54
	s_add_i32 s33, 0, 0x10424
	s_add_i32 s1, s29, -1
	s_mov_b32 s28, 0
	s_branch .LBB0_52

.LBB0_1291:
	s_or_b64 exec, exec, s[26:27]
	v_readlane_b32 s0, v254, 27
	s_waitcnt lgkmcnt(0)
	s_barrier
	v_mov_b32_e32 v10, 0x10540
	ds_read_b32 v46, v10
	v_mov_b32_e32 v11, 0x10424
	ds_read_b32 v47, v11
	ds_read_b32 v48, v11 offset:40
	ds_read_b32 v49, v11 offset:80
	ds_read_b32 v50, v11 offset:120
	ds_read_b32 v51, v11 offset:160
	ds_read_b32 v52, v11 offset:200
	ds_read_b32 v53, v11 offset:240
	v_mov_b32_e32 v9, 0x10400
	ds_read_b64 v[54:55], v9
	v_readlane_b32 s0, v252, 59
	v_readlane_b32 s1, v252, 60
	s_load_dword s28, s[0:1], 0x0
	v_readlane_b32 s16, v252, 58
	s_waitcnt lgkmcnt(0)
	v_readfirstlane_b32 s34, v46
	v_readfirstlane_b32 s35, v47
	v_readfirstlane_b32 s36, v48
	v_readfirstlane_b32 s37, v49
	v_readfirstlane_b32 s38, v50
	v_readfirstlane_b32 s39, v51
	v_readfirstlane_b32 s40, v52
	v_readfirstlane_b32 s41, v53
	v_readfirstlane_b32 s24, v54
	v_readfirstlane_b32 s25, v55
	s_nop 3
	s_add_i32 s34, s34, -1
	s_mov_b32 s33, s35
	s_cmp_eq_u32 s34, 1
	s_cselect_b32 s33, s36, s33
	s_cmp_eq_u32 s34, 2
	s_cselect_b32 s33, s37, s33
	s_cmp_eq_u32 s34, 3
	s_cselect_b32 s33, s38, s33
	s_cmp_eq_u32 s34, 4
	s_cselect_b32 s33, s39, s33
	s_cmp_eq_u32 s34, 5
	s_cselect_b32 s33, s40, s33
	s_cmp_eq_u32 s34, 6
	s_cselect_b32 s33, s41, s33
	s_lshr_b32 s0, s16, 4
	s_cmp_ge_i32 s0, s33
	s_cbranch_scc1 .Lcw_exit
	v_lshrrev_b32_e32 v1, 4, v155
	v_and_b32_e32 v2, 15, v155
	v_lshlrev_b32_e32 v2, 4, v2
	v_lshrrev_b32_e32 v4, 3, v155
	v_and_b32_e32 v5, 7, v155
	v_lshlrev_b32_e32 v5, 4, v5
	v_bfe_u32 v10, v4, 2, 1
	v_lshlrev_b32_e32 v6, 4, v10
	v_bfe_u32 v10, v4, 3, 2
	v_lshl_add_u32 v6, v10, 2, v6
	v_and_b32_e32 v10, 3, v4
	v_add_u32_e32 v6, v6, v10
	v_and_b32_e32 v10, 32, v4
	v_add_u32_e32 v6, v6, v10
	s_movk_i32 s42, 0x104
	v_mad_u32_u24 v3, v1, s42, v2
	v_add_u32_e32 v40, 0x2080, v3
	v_add_u32_e32 v41, 0x4100, v3
	v_add_u32_e32 v42, 0x4100, v40
	v_and_b32_e32 v10, 7, v155
	s_movk_i32 s42, 0x820
	v_mul_u32_u24_e32 v10, s42, v10
	v_lshl_add_u32 v7, v4, 2, v10
	v_add_u32_e32 v43, 0x410, v7
	v_add_u32_e32 v44, 0x4100, v7
	v_add_u32_e32 v45, 0x4100, v43
	s_mov_b32 s29, s0
	s_cmp_ge_i32 s29, s33
	s_cbranch_scc1 .Lcw_ip1
	s_mov_b32 s42, 0
	s_cmp_ge_i32 s29, s35
	s_cselect_b32 s43, 1, 0
	s_cmp_gt_u32 s34, 0
	s_cselect_b32 s43, s43, 0
	s_add_i32 s42, s42, s43
	s_cmp_ge_i32 s29, s36
	s_cselect_b32 s43, 1, 0
	s_cmp_gt_u32 s34, 1
	s_cselect_b32 s43, s43, 0
	s_add_i32 s42, s42, s43
	s_cmp_ge_i32 s29, s37
	s_cselect_b32 s43, 1, 0
	s_cmp_gt_u32 s34, 2
	s_cselect_b32 s43, s43, 0
	s_add_i32 s42, s42, s43
	s_cmp_ge_i32 s29, s38
	s_cselect_b32 s43, 1, 0
	s_cmp_gt_u32 s34, 3
	s_cselect_b32 s43, s43, 0
	s_add_i32 s42, s42, s43
	s_cmp_ge_i32 s29, s39
	s_cselect_b32 s43, 1, 0
	s_cmp_gt_u32 s34, 4
	s_cselect_b32 s43, s43, 0
	s_add_i32 s42, s42, s43
	s_cmp_ge_i32 s29, s40
	s_cselect_b32 s43, 1, 0
	s_cmp_gt_u32 s34, 5
	s_cselect_b32 s43, s43, 0
	s_add_i32 s42, s42, s43
	s_mul_i32 s42, s42, 40
	s_add_i32 s42, s42, 0x10400
	v_mov_b32_e32 v10, s42
	ds_read_b64 v[46:47], v10
	ds_read_b64 v[48:49], v10 offset:8
	ds_read_b64 v[50:51], v10 offset:16
	ds_read_b64 v[52:53], v10 offset:24
	ds_read_b32 v54, v10 offset:32
	s_waitcnt lgkmcnt(0)
	v_readfirstlane_b32 s24, v46
	v_readfirstlane_b32 s25, v47
	v_readfirstlane_b32 s26, v48
	v_readfirstlane_b32 s27, v49
	v_readfirstlane_b32 s2, v50
	v_readfirstlane_b32 s7, v51
	v_readfirstlane_b32 s100, v52
	v_readfirstlane_b32 s17, v53
	v_readfirstlane_b32 s101, v54
	s_nop 3
	s_sub_i32 s43, s29, s101
	s_lshr_b32 s100, s100, 6
	s_movk_i32 s101, 0x1000
	s_cmp_eq_u32 s100, 24
	s_cselect_b32 s101, 0xaab, s101
	s_cmp_eq_u32 s100, 44
	s_cselect_b32 s101, 0x5d2, s101
	s_mul_i32 s1, s43, s101
	s_lshr_b32 s1, s1, 16
	s_mul_i32 s16, s1, s100
	s_sub_i32 s16, s43, s16
	s_mul_i32 s42, s1, s2
	s_lshl_b32 s42, s42, 8
	s_lshl_b32 s43, s16, 8
	s_add_u32 s42, s42, s43
	s_add_u32 s24, s24, s42
	s_addc_u32 s25, s25, 0
	s_lshl_b32 s43, s2, 7
	s_add_u32 s26, s24, s43
	s_addc_u32 s27, s25, 0
	s_lshl_b32 s43, s2, 2
	v_mad_u32_u24 v8, v1, s43, v2
.Lcw_ip1:
	s_cmp_ge_i32 s29, s33
	s_cbranch_scc1 .Lcw_dm2
	global_load_dwordx4 v[12:15], v8, s[24:25] nt
	global_load_dwordx4 v[16:19], v8, s[26:27] nt
	s_branch .Lcw_dn3
.Lcw_dm2:
	global_load_dwordx4 v[12:15], v2, s[24:25]
	global_load_dwordx4 v[16:19], v2, s[24:25]
.Lcw_dn3:
	s_add_i32 s29, s29, s28
	s_cmp_ge_i32 s29, s33
	s_cbranch_scc1 .Lcw_ip4
	s_mov_b32 s42, 0
	s_cmp_ge_i32 s29, s35
	s_cselect_b32 s43, 1, 0
	s_cmp_gt_u32 s34, 0
	s_cselect_b32 s43, s43, 0
	s_add_i32 s42, s42, s43
	s_cmp_ge_i32 s29, s36
	s_cselect_b32 s43, 1, 0
	s_cmp_gt_u32 s34, 1
	s_cselect_b32 s43, s43, 0
	s_add_i32 s42, s42, s43
	s_cmp_ge_i32 s29, s37
	s_cselect_b32 s43, 1, 0
	s_cmp_gt_u32 s34, 2
	s_cselect_b32 s43, s43, 0
	s_add_i32 s42, s42, s43
	s_cmp_ge_i32 s29, s38
	s_cselect_b32 s43, 1, 0
	s_cmp_gt_u32 s34, 3
	s_cselect_b32 s43, s43, 0
	s_add_i32 s42, s42, s43
	s_cmp_ge_i32 s29, s39
	s_cselect_b32 s43, 1, 0
	s_cmp_gt_u32 s34, 4
	s_cselect_b32 s43, s43, 0
	s_add_i32 s42, s42, s43
	s_cmp_ge_i32 s29, s40
	s_cselect_b32 s43, 1, 0
	s_cmp_gt_u32 s34, 5
	s_cselect_b32 s43, s43, 0
	s_add_i32 s42, s42, s43
	s_mul_i32 s42, s42, 40
	s_add_i32 s42, s42, 0x10400
	v_mov_b32_e32 v10, s42
	ds_read_b64 v[46:47], v10
	ds_read_b64 v[48:49], v10 offset:8
	ds_read_b64 v[50:51], v10 offset:16
	ds_read_b64 v[52:53], v10 offset:24
	ds_read_b32 v54, v10 offset:32
	s_waitcnt lgkmcnt(0)
	v_readfirstlane_b32 s24, v46
	v_readfirstlane_b32 s25, v47
	v_readfirstlane_b32 s26, v48
	v_readfirstlane_b32 s27, v49
	v_readfirstlane_b32 s2, v50
	v_readfirstlane_b32 s7, v51
	v_readfirstlane_b32 s100, v52
	v_readfirstlane_b32 s17, v53
	v_readfirstlane_b32 s101, v54
	s_nop 3
	s_sub_i32 s43, s29, s101
	s_lshr_b32 s100, s100, 6
	s_movk_i32 s101, 0x1000
	s_cmp_eq_u32 s100, 24
	s_cselect_b32 s101, 0xaab, s101
	s_cmp_eq_u32 s100, 44
	s_cselect_b32 s101, 0x5d2, s101
	s_mul_i32 s1, s43, s101
	s_lshr_b32 s1, s1, 16
	s_mul_i32 s16, s1, s100
	s_sub_i32 s16, s43, s16
	s_mul_i32 s42, s1, s2
	s_lshl_b32 s42, s42, 8
	s_lshl_b32 s43, s16, 8
	s_add_u32 s42, s42, s43
	s_add_u32 s24, s24, s42
	s_addc_u32 s25, s25, 0
	s_lshl_b32 s43, s2, 7
	s_add_u32 s26, s24, s43
	s_addc_u32 s27, s25, 0
	s_lshl_b32 s43, s2, 2
	v_mad_u32_u24 v8, v1, s43, v2
.Lcw_ip4:
	s_cmp_ge_i32 s29, s33
	s_cbranch_scc1 .Lcw_dm5
	global_load_dwordx4 v[20:23], v8, s[24:25] nt
	global_load_dwordx4 v[24:27], v8, s[26:27] nt
	s_branch .Lcw_dn6
.Lcw_dm5:
	global_load_dwordx4 v[20:23], v2, s[24:25]
	global_load_dwordx4 v[24:27], v2, s[24:25]
.Lcw_dn6:
	s_add_i32 s29, s29, s28
	s_mov_b32 s42, 0
	s_cmp_ge_i32 s0, s35
	s_cselect_b32 s43, 1, 0
	s_cmp_gt_u32 s34, 0
	s_cselect_b32 s43, s43, 0
	s_add_i32 s42, s42, s43
	s_cmp_ge_i32 s0, s36
	s_cselect_b32 s43, 1, 0
	s_cmp_gt_u32 s34, 1
	s_cselect_b32 s43, s43, 0
	s_add_i32 s42, s42, s43
	s_cmp_ge_i32 s0, s37
	s_cselect_b32 s43, 1, 0
	s_cmp_gt_u32 s34, 2
	s_cselect_b32 s43, s43, 0
	s_add_i32 s42, s42, s43
	s_cmp_ge_i32 s0, s38
	s_cselect_b32 s43, 1, 0
	s_cmp_gt_u32 s34, 3
	s_cselect_b32 s43, s43, 0
	s_add_i32 s42, s42, s43
	s_cmp_ge_i32 s0, s39
	s_cselect_b32 s43, 1, 0
	s_cmp_gt_u32 s34, 4
	s_cselect_b32 s43, s43, 0
	s_add_i32 s42, s42, s43
	s_cmp_ge_i32 s0, s40
	s_cselect_b32 s43, 1, 0
	s_cmp_gt_u32 s34, 5
	s_cselect_b32 s43, s43, 0
	s_add_i32 s42, s42, s43
	s_mul_i32 s42, s42, 40
	s_add_i32 s42, s42, 0x10400
	v_mov_b32_e32 v10, s42
	ds_read_b64 v[46:47], v10
	ds_read_b64 v[48:49], v10 offset:8
	ds_read_b64 v[50:51], v10 offset:16
	ds_read_b64 v[52:53], v10 offset:24
	ds_read_b32 v54, v10 offset:32
	s_waitcnt lgkmcnt(0)
	v_readfirstlane_b32 s24, v46
	v_readfirstlane_b32 s25, v47
	v_readfirstlane_b32 s26, v48
	v_readfirstlane_b32 s27, v49
	v_readfirstlane_b32 s2, v50
	v_readfirstlane_b32 s7, v51
	v_readfirstlane_b32 s100, v52
	v_readfirstlane_b32 s17, v53
	v_readfirstlane_b32 s101, v54
	s_nop 3
	s_sub_i32 s43, s0, s101
	s_lshr_b32 s100, s100, 6
	s_movk_i32 s101, 0x1000
	s_cmp_eq_u32 s100, 24
	s_cselect_b32 s101, 0xaab, s101
	s_cmp_eq_u32 s100, 44
	s_cselect_b32 s101, 0x5d2, s101
	s_mul_i32 s1, s43, s101
	s_lshr_b32 s1, s1, 16
	s_mul_i32 s16, s1, s100
	s_sub_i32 s16, s43, s16
	s_lshl_b32 s42, s16, 6
	s_mov_b32 vcc_lo, 1
	s_cmp_eq_u32 s17, 3
	s_cselect_b32 s43, 1, 0
	s_cmp_ge_u32 s16, 16
	s_cselect_b32 s43, s43, 0
	s_cmp_eq_u32 s43, 1
	s_cselect_b32 vcc_lo, 0, vcc_lo
	s_lshr_b32 s43, s16, 1
	s_lshl_b32 s43, s43, 8
	s_and_b32 vcc_hi, s16, 1
	s_lshl_b32 vcc_hi, vcc_hi, 6
	s_add_i32 s43, s43, vcc_hi
	s_cmp_eq_u32 s17, 1
	s_cselect_b32 s42, s43, s42
	s_add_i32 s43, s43, 0x80
	s_cmp_eq_u32 s17, 2
	s_cselect_b32 s42, s43, s42
	s_mul_i32 s42, s42, s7
	s_lshl_b32 s43, s1, 6
	s_add_i32 s42, s42, s43
	s_lshl_b32 s42, s42, 1
	s_add_u32 s26, s26, s42
	s_addc_u32 s27, s27, 0
	s_cmp_eq_u32 vcc_lo, 0
	s_cbranch_scc1 .Lcw_pl7
	v_mov_b32_e32 v11, v6
	s_branch .Lcw_pd8

.Lcw_pd8:
	s_lshl_b32 s43, s7, 1
	v_mad_u32_u24 v9, v11, s43, v5
	s_mov_b64 s[44:45], s[26:27]
	s_cmp_ge_i32 s29, s33
	s_cbranch_scc1 .Lcw_ip9
	s_mov_b32 s42, 0
	s_cmp_ge_i32 s29, s35
	s_cselect_b32 s43, 1, 0
	s_cmp_gt_u32 s34, 0
	s_cselect_b32 s43, s43, 0
	s_add_i32 s42, s42, s43
	s_cmp_ge_i32 s29, s36
	s_cselect_b32 s43, 1, 0
	s_cmp_gt_u32 s34, 1
	s_cselect_b32 s43, s43, 0
	s_add_i32 s42, s42, s43
	s_cmp_ge_i32 s29, s37
	s_cselect_b32 s43, 1, 0
	s_cmp_gt_u32 s34, 2
	s_cselect_b32 s43, s43, 0
	s_add_i32 s42, s42, s43
	s_cmp_ge_i32 s29, s38
	s_cselect_b32 s43, 1, 0
	s_cmp_gt_u32 s34, 3
	s_cselect_b32 s43, s43, 0
	s_add_i32 s42, s42, s43
	s_cmp_ge_i32 s29, s39
	s_cselect_b32 s43, 1, 0
	s_cmp_gt_u32 s34, 4
	s_cselect_b32 s43, s43, 0
	s_add_i32 s42, s42, s43
	s_cmp_ge_i32 s29, s40
	s_cselect_b32 s43, 1, 0
	s_cmp_gt_u32 s34, 5
	s_cselect_b32 s43, s43, 0
	s_add_i32 s42, s42, s43
	s_mul_i32 s42, s42, 40
	s_add_i32 s42, s42, 0x10400
	v_mov_b32_e32 v10, s42
	ds_read_b64 v[46:47], v10
	ds_read_b64 v[48:49], v10 offset:8
	ds_read_b64 v[50:51], v10 offset:16
	ds_read_b64 v[52:53], v10 offset:24
	ds_read_b32 v54, v10 offset:32
	s_waitcnt lgkmcnt(0)
	v_readfirstlane_b32 s24, v46
	v_readfirstlane_b32 s25, v47
	v_readfirstlane_b32 s26, v48
	v_readfirstlane_b32 s27, v49
	v_readfirstlane_b32 s2, v50
	v_readfirstlane_b32 s7, v51
	v_readfirstlane_b32 s100, v52
	v_readfirstlane_b32 s17, v53
	v_readfirstlane_b32 s101, v54
	s_nop 3
	s_sub_i32 s43, s29, s101
	s_lshr_b32 s100, s100, 6
	s_movk_i32 s101, 0x1000
	s_cmp_eq_u32 s100, 24
	s_cselect_b32 s101, 0xaab, s101
	s_cmp_eq_u32 s100, 44
	s_cselect_b32 s101, 0x5d2, s101
	s_mul_i32 s1, s43, s101
	s_lshr_b32 s1, s1, 16
	s_mul_i32 s16, s1, s100
	s_sub_i32 s16, s43, s16
	s_mul_i32 s42, s1, s2
	s_lshl_b32 s42, s42, 8
	s_lshl_b32 s43, s16, 8
	s_add_u32 s42, s42, s43
	s_add_u32 s24, s24, s42
	s_addc_u32 s25, s25, 0
	s_lshl_b32 s43, s2, 7
	s_add_u32 s26, s24, s43
	s_addc_u32 s27, s25, 0
	s_lshl_b32 s43, s2, 2
	v_mad_u32_u24 v8, v1, s43, v2
.Lcw_ip9:
	s_waitcnt vmcnt(2)
	ds_write2_b32 v3, v12, v13 offset1:1
	ds_write2_b32 v3, v14, v15 offset0:2 offset1:3
	ds_write2_b32 v40, v16, v17 offset1:1
	ds_write2_b32 v40, v18, v19 offset0:2 offset1:3
	s_cmp_ge_i32 s29, s33
	s_cbranch_scc1 .Lcw_dm10
	global_load_dwordx4 v[12:15], v8, s[24:25] nt
	global_load_dwordx4 v[16:19], v8, s[26:27] nt
	s_branch .Lcw_dn11

.Lcw_dn11:
	s_waitcnt lgkmcnt(0)
	s_barrier
	s_add_i32 s29, s29, s28
	ds_read2_b32 v[28:29], v7 offset1:65
	ds_read2_b32 v[30:31], v7 offset0:130 offset1:195
	ds_read2_b32 v[32:33], v43 offset1:65
	ds_read2_b32 v[34:35], v43 offset0:130 offset1:195
	s_waitcnt lgkmcnt(0)
	v_cvt_pk_bf16_f32 v36, v28, v29
	v_cvt_pk_bf16_f32 v37, v30, v31
	v_cvt_pk_bf16_f32 v38, v32, v33
	v_cvt_pk_bf16_f32 v39, v34, v35
	global_store_dwordx4 v9, v[36:39], s[44:45]
	s_add_i32 s0, s0, s28
	s_cmp_ge_i32 s0, s33
	s_cbranch_scc1 .Lcw_exit
	s_mov_b32 s42, 0
	s_cmp_ge_i32 s0, s35
	s_cselect_b32 s43, 1, 0
	s_cmp_gt_u32 s34, 0
	s_cselect_b32 s43, s43, 0
	s_add_i32 s42, s42, s43
	s_cmp_ge_i32 s0, s36
	s_cselect_b32 s43, 1, 0
	s_cmp_gt_u32 s34, 1
	s_cselect_b32 s43, s43, 0
	s_add_i32 s42, s42, s43
	s_cmp_ge_i32 s0, s37
	s_cselect_b32 s43, 1, 0
	s_cmp_gt_u32 s34, 2
	s_cselect_b32 s43, s43, 0
	s_add_i32 s42, s42, s43
	s_cmp_ge_i32 s0, s38
	s_cselect_b32 s43, 1, 0
	s_cmp_gt_u32 s34, 3
	s_cselect_b32 s43, s43, 0
	s_add_i32 s42, s42, s43
	s_cmp_ge_i32 s0, s39
	s_cselect_b32 s43, 1, 0
	s_cmp_gt_u32 s34, 4
	s_cselect_b32 s43, s43, 0
	s_add_i32 s42, s42, s43
	s_cmp_ge_i32 s0, s40
	s_cselect_b32 s43, 1, 0
	s_cmp_gt_u32 s34, 5
	s_cselect_b32 s43, s43, 0
	s_add_i32 s42, s42, s43
	s_mul_i32 s42, s42, 40
	s_add_i32 s42, s42, 0x10400
	v_mov_b32_e32 v10, s42
	ds_read_b64 v[46:47], v10
	ds_read_b64 v[48:49], v10 offset:8
	ds_read_b64 v[50:51], v10 offset:16
	ds_read_b64 v[52:53], v10 offset:24
	ds_read_b32 v54, v10 offset:32
	s_waitcnt lgkmcnt(0)
	v_readfirstlane_b32 s24, v46
	v_readfirstlane_b32 s25, v47
	v_readfirstlane_b32 s26, v48
	v_readfirstlane_b32 s27, v49
	v_readfirstlane_b32 s2, v50
	v_readfirstlane_b32 s7, v51
	v_readfirstlane_b32 s100, v52
	v_readfirstlane_b32 s17, v53
	v_readfirstlane_b32 s101, v54
	s_nop 3
	s_sub_i32 s43, s0, s101
	s_lshr_b32 s100, s100, 6
	s_movk_i32 s101, 0x1000
	s_cmp_eq_u32 s100, 24
	s_cselect_b32 s101, 0xaab, s101
	s_cmp_eq_u32 s100, 44
	s_cselect_b32 s101, 0x5d2, s101
	s_mul_i32 s1, s43, s101
	s_lshr_b32 s1, s1, 16
	s_mul_i32 s16, s1, s100
	s_sub_i32 s16, s43, s16
	s_lshl_b32 s42, s16, 6
	s_mov_b32 vcc_lo, 1
	s_cmp_eq_u32 s17, 3
	s_cselect_b32 s43, 1, 0
	s_cmp_ge_u32 s16, 16
	s_cselect_b32 s43, s43, 0
	s_cmp_eq_u32 s43, 1
	s_cselect_b32 vcc_lo, 0, vcc_lo
	s_lshr_b32 s43, s16, 1
	s_lshl_b32 s43, s43, 8
	s_and_b32 vcc_hi, s16, 1
	s_lshl_b32 vcc_hi, vcc_hi, 6
	s_add_i32 s43, s43, vcc_hi
	s_cmp_eq_u32 s17, 1
	s_cselect_b32 s42, s43, s42
	s_add_i32 s43, s43, 0x80
	s_cmp_eq_u32 s17, 2
	s_cselect_b32 s42, s43, s42
	s_mul_i32 s42, s42, s7
	s_lshl_b32 s43, s1, 6
	s_add_i32 s42, s42, s43
	s_lshl_b32 s42, s42, 1
	s_add_u32 s26, s26, s42
	s_addc_u32 s27, s27, 0
	s_cmp_eq_u32 vcc_lo, 0
	s_cbranch_scc1 .Lcw_pl12
	v_mov_b32_e32 v11, v6
	s_branch .Lcw_pd13

.Lcw_ip14:
	s_waitcnt vmcnt(3)
	ds_write2_b32 v41, v20, v21 offset1:1
	ds_write2_b32 v41, v22, v23 offset0:2 offset1:3
	ds_write2_b32 v42, v24, v25 offset1:1
	ds_write2_b32 v42, v26, v27 offset0:2 offset1:3
	s_cmp_ge_i32 s29, s33
	s_cbranch_scc1 .Lcw_dm15
	global_load_dwordx4 v[20:23], v8, s[24:25] nt
	global_load_dwordx4 v[24:27], v8, s[26:27] nt
	s_branch .Lcw_dn16

.Lcw_dn16:
	s_waitcnt lgkmcnt(0)
	s_barrier
	s_add_i32 s29, s29, s28
	ds_read2_b32 v[28:29], v44 offset1:65
	ds_read2_b32 v[30:31], v44 offset0:130 offset1:195
	ds_read2_b32 v[32:33], v45 offset1:65
	ds_read2_b32 v[34:35], v45 offset0:130 offset1:195
	s_waitcnt lgkmcnt(0)
	v_cvt_pk_bf16_f32 v36, v28, v29
	v_cvt_pk_bf16_f32 v37, v30, v31
	v_cvt_pk_bf16_f32 v38, v32, v33
	v_cvt_pk_bf16_f32 v39, v34, v35
	global_store_dwordx4 v9, v[36:39], s[44:45]
	s_add_i32 s0, s0, s28
	s_cmp_ge_i32 s0, s33
	s_cbranch_scc1 .Lcw_exit
.Lcw_loop:
	s_mov_b32 s42, 0
	s_cmp_ge_i32 s0, s35
	s_cselect_b32 s43, 1, 0
	s_cmp_gt_u32 s34, 0
	s_cselect_b32 s43, s43, 0
	s_add_i32 s42, s42, s43
	s_cmp_ge_i32 s0, s36
	s_cselect_b32 s43, 1, 0
	s_cmp_gt_u32 s34, 1
	s_cselect_b32 s43, s43, 0
	s_add_i32 s42, s42, s43
	s_cmp_ge_i32 s0, s37
	s_cselect_b32 s43, 1, 0
	s_cmp_gt_u32 s34, 2
	s_cselect_b32 s43, s43, 0
	s_add_i32 s42, s42, s43
	s_cmp_ge_i32 s0, s38
	s_cselect_b32 s43, 1, 0
	s_cmp_gt_u32 s34, 3
	s_cselect_b32 s43, s43, 0
	s_add_i32 s42, s42, s43
	s_cmp_ge_i32 s0, s39
	s_cselect_b32 s43, 1, 0
	s_cmp_gt_u32 s34, 4
	s_cselect_b32 s43, s43, 0
	s_add_i32 s42, s42, s43
	s_cmp_ge_i32 s0, s40
	s_cselect_b32 s43, 1, 0
	s_cmp_gt_u32 s34, 5
	s_cselect_b32 s43, s43, 0
	s_add_i32 s42, s42, s43
	s_mul_i32 s42, s42, 40
	s_add_i32 s42, s42, 0x10400
	v_mov_b32_e32 v10, s42
	ds_read_b64 v[46:47], v10
	ds_read_b64 v[48:49], v10 offset:8
	ds_read_b64 v[50:51], v10 offset:16
	ds_read_b64 v[52:53], v10 offset:24
	ds_read_b32 v54, v10 offset:32
	s_waitcnt lgkmcnt(0)
	v_readfirstlane_b32 s24, v46
	v_readfirstlane_b32 s25, v47
	v_readfirstlane_b32 s26, v48
	v_readfirstlane_b32 s27, v49
	v_readfirstlane_b32 s2, v50
	v_readfirstlane_b32 s7, v51
	v_readfirstlane_b32 s100, v52
	v_readfirstlane_b32 s17, v53
	v_readfirstlane_b32 s101, v54
	s_nop 3
	s_sub_i32 s43, s0, s101
	s_lshr_b32 s100, s100, 6
	s_movk_i32 s101, 0x1000
	s_cmp_eq_u32 s100, 24
	s_cselect_b32 s101, 0xaab, s101
	s_cmp_eq_u32 s100, 44
	s_cselect_b32 s101, 0x5d2, s101
	s_mul_i32 s1, s43, s101
	s_lshr_b32 s1, s1, 16
	s_mul_i32 s16, s1, s100
	s_sub_i32 s16, s43, s16
	s_lshl_b32 s42, s16, 6
	s_mov_b32 vcc_lo, 1
	s_cmp_eq_u32 s17, 3
	s_cselect_b32 s43, 1, 0
	s_cmp_ge_u32 s16, 16
	s_cselect_b32 s43, s43, 0
	s_cmp_eq_u32 s43, 1
	s_cselect_b32 vcc_lo, 0, vcc_lo
	s_lshr_b32 s43, s16, 1
	s_lshl_b32 s43, s43, 8
	s_and_b32 vcc_hi, s16, 1
	s_lshl_b32 vcc_hi, vcc_hi, 6
	s_add_i32 s43, s43, vcc_hi
	s_cmp_eq_u32 s17, 1
	s_cselect_b32 s42, s43, s42
	s_add_i32 s43, s43, 0x80
	s_cmp_eq_u32 s17, 2
	s_cselect_b32 s42, s43, s42
	s_mul_i32 s42, s42, s7
	s_lshl_b32 s43, s1, 6
	s_add_i32 s42, s42, s43
	s_lshl_b32 s42, s42, 1
	s_add_u32 s26, s26, s42
	s_addc_u32 s27, s27, 0
	s_cmp_eq_u32 vcc_lo, 0
	s_cbranch_scc1 .Lcw_pl17
	v_mov_b32_e32 v11, v6
	s_branch .Lcw_pd18

.Lcw_ip19:
	s_waitcnt vmcnt(4)
	ds_write2_b32 v3, v12, v13 offset1:1
	ds_write2_b32 v3, v14, v15 offset0:2 offset1:3
	ds_write2_b32 v40, v16, v17 offset1:1
	ds_write2_b32 v40, v18, v19 offset0:2 offset1:3
	s_cmp_ge_i32 s29, s33
	s_cbranch_scc1 .Lcw_dm20
	global_load_dwordx4 v[12:15], v8, s[24:25] nt
	global_load_dwordx4 v[16:19], v8, s[26:27] nt
	s_branch .Lcw_dn21

.Lcw_ip24:
	s_waitcnt vmcnt(4)
	ds_write2_b32 v41, v20, v21 offset1:1
	ds_write2_b32 v41, v22, v23 offset0:2 offset1:3
	ds_write2_b32 v42, v24, v25 offset1:1
	ds_write2_b32 v42, v26, v27 offset0:2 offset1:3
	s_cmp_ge_i32 s29, s33
	s_cbranch_scc1 .Lcw_dm25
	global_load_dwordx4 v[20:23], v8, s[24:25] nt
	global_load_dwordx4 v[24:27], v8, s[26:27] nt
	s_branch .Lcw_dn26

.Lcw_dn26:
	s_waitcnt lgkmcnt(0)
	s_barrier
	s_add_i32 s29, s29, s28
	ds_read2_b32 v[28:29], v44 offset1:65
	ds_read2_b32 v[30:31], v44 offset0:130 offset1:195
	ds_read2_b32 v[32:33], v45 offset1:65
	ds_read2_b32 v[34:35], v45 offset0:130 offset1:195
	s_waitcnt lgkmcnt(0)
	v_cvt_pk_bf16_f32 v36, v28, v29
	v_cvt_pk_bf16_f32 v37, v30, v31
	v_cvt_pk_bf16_f32 v38, v32, v33
	v_cvt_pk_bf16_f32 v39, v34, v35
	global_store_dwordx4 v9, v[36:39], s[44:45]
	s_add_i32 s0, s0, s28
	s_cmp_ge_i32 s0, s33
	s_cbranch_scc1 .Lcw_exit
	s_branch .Lcw_loop
.Lcw_exit:
	s_branch .LBB0_1350
	v_mov_b32_e32 v0, s0
	ds_read_b32 v0, v0
	v_readlane_b32 s16, v254, 52
	v_mov_b32_e32 v3, 0
	v_mov_b32_e32 v29, 0
	v_mov_b32_e32 v28, 0
	s_waitcnt lgkmcnt(0)
	v_mul_lo_u32 v1, v0, 40
	v_add_u32_e32 v1, 0, v1
	v_add_u32_e32 v1, 0x103fc, v1
	ds_read_b32 v5, v1
	v_mov_b32_e32 v1, 0
	v_readfirstlane_b32 s7, v0
	v_mov_b32_e32 v27, 0
	v_mov_b32_e32 v26, 0
	s_waitcnt lgkmcnt(0)
	v_cmp_ge_i32_e32 vcc, s16, v5
	v_readfirstlane_b32 s0, v5
	v_cmp_lt_i32_e64 s[40:41], s16, v5
	v_mov_b32_e32 v25, 0
	v_mov_b32_e32 v24, 0
	v_readlane_b32 s17, v254, 53
	s_cbranch_vccnz .LBB0_1298
	s_cmp_lt_i32 s7, 2
	s_mov_b32 s28, 0
	s_cbranch_scc1 .LBB0_1297
	s_add_i32 s27, 0, 0x10424
	s_add_i32 s1, s7, -1
	s_mov_b32 s26, 0
	s_branch .LBB0_1295

	.amdhsa_kernel _Z10mk_forward6Paramsii
		.amdhsa_group_segment_fixed_size 0
		.amdhsa_private_segment_fixed_size 0
		.amdhsa_kernarg_size 512
		.amdhsa_user_sgpr_count 2
		.amdhsa_user_sgpr_dispatch_ptr 0
		.amdhsa_user_sgpr_queue_ptr 0
		.amdhsa_user_sgpr_kernarg_segment_ptr 1
		.amdhsa_user_sgpr_dispatch_id 0
		.amdhsa_user_sgpr_kernarg_preload_length 0
		.amdhsa_user_sgpr_kernarg_preload_offset 0
		.amdhsa_user_sgpr_private_segment_size 0
		.amdhsa_uses_dynamic_stack 0
		.amdhsa_enable_private_segment 0
		.amdhsa_system_sgpr_workgroup_id_x 1
		.amdhsa_system_sgpr_workgroup_id_y 0
		.amdhsa_system_sgpr_workgroup_id_z 0
		.amdhsa_system_sgpr_workgroup_info 0
		.amdhsa_system_vgpr_workitem_id 2
		.amdhsa_next_free_vgpr 256
		.amdhsa_next_free_sgpr 102
		.amdhsa_accum_offset 256
		.amdhsa_reserve_vcc 1
		.amdhsa_float_round_mode_32 0
		.amdhsa_float_round_mode_16_64 0
		.amdhsa_float_denorm_mode_32 3
		.amdhsa_float_denorm_mode_16_64 3
		.amdhsa_dx10_clamp 1
		.amdhsa_ieee_mode 1
		.amdhsa_fp16_overflow 0
		.amdhsa_tg_split 0
		.amdhsa_exception_fp_ieee_invalid_op 0
		.amdhsa_exception_fp_denorm_src 0
		.amdhsa_exception_fp_ieee_div_zero 0
		.amdhsa_exception_fp_ieee_overflow 0
		.amdhsa_exception_fp_ieee_underflow 0
		.amdhsa_exception_fp_ieee_inexact 0
		.amdhsa_exception_int_div_zero 0
	.end_amdhsa_kernel

amdhsa.kernels:
  - .agpr_count:     0
    .args:
      - .offset:         0
        .size:           248
        .value_kind:     by_value
      - .offset:         248
        .size:           4
        .value_kind:     by_value
      - .offset:         252
        .size:           4
        .value_kind:     by_value
      - .offset:         256
        .size:           4
        .value_kind:     hidden_block_count_x
      - .offset:         260
        .size:           4
        .value_kind:     hidden_block_count_y
      - .offset:         264
        .size:           4
        .value_kind:     hidden_block_count_z
      - .offset:         268
        .size:           2
        .value_kind:     hidden_group_size_x
      - .offset:         270
        .size:           2
        .value_kind:     hidden_group_size_y
      - .offset:         272
        .size:           2
        .value_kind:     hidden_group_size_z
      - .offset:         274
        .size:           2
        .value_kind:     hidden_remainder_x
      - .offset:         276
        .size:           2
        .value_kind:     hidden_remainder_y
      - .offset:         278
        .size:           2
        .value_kind:     hidden_remainder_z
      - .offset:         296
        .size:           8
        .value_kind:     hidden_global_offset_x
      - .offset:         304
        .size:           8
        .value_kind:     hidden_global_offset_y
      - .offset:         312
        .size:           8
        .value_kind:     hidden_global_offset_z
      - .offset:         320
        .size:           2
        .value_kind:     hidden_grid_dims
      - .offset:         344
        .size:           8
        .value_kind:     hidden_multigrid_sync_arg
      - .offset:         376
        .size:           4
        .value_kind:     hidden_dynamic_lds_size
    .group_segment_fixed_size: 0
    .kernarg_segment_align: 8
    .kernarg_segment_size: 512
    .language:       OpenCL C
    .language_version:
      - 2
      - 0
    .max_flat_workgroup_size: 512
    .name:           _Z10mk_forward6Paramsii
    .private_segment_fixed_size: 0
    .sgpr_count:     108
    .sgpr_spill_count: 221
    .symbol:         _Z10mk_forward6Paramsii.kd
    .uniform_work_group_size: 1
    .uses_dynamic_stack: false
    .vgpr_count:     256
    .vgpr_spill_count: 0
    .wavefront_size: 64
